# strategy 8 (MFMA/LDS interleave): MLA tile-end staging ds_writes, their address VALU and pointer increments moved into the shadow of the 8 PV MFMAs
# baseline (speedup 1.0000x reference)
; #define MFMA(a, b, c) __builtin_amdgcn_mfma_f32_32x32x16_bf16((a), (b), (c), 0, 0, 0)
; DI unsigned pack2(float a, float b) { f32x2 v = {a, b}; return __builtin_bit_cast(unsigned, __builtin_convertvector(v, bf16v2)); }
; template <int DK, int MODE> ...
;     ...
;           s0[e] = __builtin_amdgcn_exp2f(s0[e] - m); s0[e + 1] = __builtin_amdgcn_exp2f(s0[e + 1] - m); s0[e + 2] = __builtin_amdgcn_exp2f(s0[e + 2] - m); s0[e + 3] = __builtin_amdgcn_exp2f(s0[e + 3] - m);
;           ps0 += s0[e]; ps1 += s0[e + 1]; ps2 += s0[e + 2]; ps3 += s0[e + 3];
;         }
; #pragma unroll
;         for (int e = 0; e < 16; e += 4) {
;           s1[e] = __builtin_amdgcn_exp2f(s1[e] - m); s1[e + 1] = __builtin_amdgcn_exp2f(s1[e + 1] - m); s1[e + 2] = __builtin_amdgcn_exp2f(s1[e + 2] - m); s1[e + 3] = __builtin_amdgcn_exp2f(s1[e + 3] - m);
;           ps0 += s1[e]; ps1 += s1[e + 1]; ps2 += s1[e + 2]; ps3 += s1[e + 3];
;         }
;         lsum += (ps0 + ps1) + (ps2 + ps3);
;     ...
; #pragma unroll
;       for (int j = 0; j < 2; ++j) {
;         u32x4 a, b;
;         a.x = pack2(s0[8 * j], s0[8 * j + 1]); a.y = pack2(s0[8 * j + 2], s0[8 * j + 3]); a.z = pack2(s0[8 * j + 4], s0[8 * j + 5]); a.w = pack2(s0[8 * j + 6], s0[8 * j + 7]);
;         b.x = pack2(s1[8 * j], s1[8 * j + 1]); b.y = pack2(s1[8 * j + 2], s1[8 * j + 3]); b.z = pack2(s1[8 * j + 4], s1[8 * j + 5]); b.w = pack2(s1[8 * j + 6], s1[8 * j + 7]);
;         pf[j] = __builtin_bit_cast(bf16x8, a); pf[2 + j] = __builtin_bit_cast(bf16x8, b);
;       }
;       __builtin_amdgcn_s_setprio(1);
; #pragma unroll
;       for (int j = 0; j < 4; ++j) { o0 = MFMA(vf0[j], pf[j], o0); o1 = MFMA(vf1[j], pf[j], o1); }
;       __builtin_amdgcn_s_setprio(0);
;     }
;     __builtin_amdgcn_sched_barrier(0);
;     if (more) swrite(cur ^ 1);
.LBB0_524:
	v_sub_f32_e32 v0, v64, v155
	v_exp_f32_e32 v14, v0
	v_sub_f32_e32 v0, v65, v155
	v_exp_f32_e32 v64, v0
	v_sub_f32_e32 v0, v66, v155
	v_exp_f32_e32 v15, v0
	v_sub_f32_e32 v0, v67, v155
	v_exp_f32_e32 v65, v0
	v_sub_f32_e32 v0, v68, v155
	v_exp_f32_e32 v66, v0
	v_sub_f32_e32 v0, v69, v155
	v_exp_f32_e32 v68, v0
	v_sub_f32_e32 v0, v70, v155
	v_exp_f32_e32 v67, v0
	v_sub_f32_e32 v0, v71, v155
	v_exp_f32_e32 v69, v0
	v_sub_f32_e32 v0, v72, v155
	v_exp_f32_e32 v70, v0
	v_sub_f32_e32 v0, v73, v155
	v_exp_f32_e32 v72, v0
	v_sub_f32_e32 v0, v74, v155
	v_exp_f32_e32 v71, v0
	v_sub_f32_e32 v0, v75, v155
	v_exp_f32_e32 v73, v0
	v_sub_f32_e32 v0, v76, v155
	v_exp_f32_e32 v74, v0
	v_sub_f32_e32 v0, v77, v155
	v_exp_f32_e32 v76, v0
	v_sub_f32_e32 v0, v78, v155
	v_exp_f32_e32 v75, v0
	v_sub_f32_e32 v0, v79, v155
	v_exp_f32_e32 v77, v0
	v_sub_f32_e32 v0, v48, v155
	v_exp_f32_e32 v78, v0
	v_sub_f32_e32 v0, v49, v155
	v_exp_f32_e32 v176, v0
	v_sub_f32_e32 v0, v50, v155
	v_exp_f32_e32 v79, v0
	v_sub_f32_e32 v0, v51, v155
	v_exp_f32_e32 v177, v0
	v_sub_f32_e32 v0, v52, v155
	v_exp_f32_e32 v178, v0
	v_sub_f32_e32 v0, v53, v155
	v_exp_f32_e32 v180, v0
	v_sub_f32_e32 v0, v54, v155
	v_exp_f32_e32 v179, v0
	v_sub_f32_e32 v0, v55, v155
	v_exp_f32_e32 v181, v0
	v_sub_f32_e32 v0, v56, v155
	v_exp_f32_e32 v182, v0
	v_sub_f32_e32 v0, v57, v155
	v_exp_f32_e32 v184, v0
	v_sub_f32_e32 v0, v58, v155
	v_exp_f32_e32 v183, v0
	v_sub_f32_e32 v0, v59, v155
	v_exp_f32_e32 v185, v0
	v_sub_f32_e32 v0, v60, v155
	v_exp_f32_e32 v186, v0
	v_sub_f32_e32 v0, v61, v155
	v_exp_f32_e32 v200, v0
	v_sub_f32_e32 v0, v62, v155
	v_pk_add_f32 v[48:49], v[66:67], v[14:15]
	v_pk_add_f32 v[50:51], v[68:69], v[64:65]
	v_exp_f32_e32 v187, v0
	v_sub_f32_e32 v0, v63, v155
	v_pk_add_f32 v[48:49], v[70:71], v[48:49]
	v_pk_add_f32 v[50:51], v[72:73], v[50:51]
	v_exp_f32_e32 v201, v0
	v_pk_add_f32 v[202:203], v[74:75], v[48:49]
	v_pk_add_f32 v[204:205], v[76:77], v[50:51]
	v_cvt_pk_bf16_f32 v48, v14, v64
	v_cvt_pk_bf16_f32 v49, v15, v65
	v_pk_add_f32 v[14:15], v[78:79], v[202:203]
	v_pk_add_f32 v[64:65], v[176:177], v[204:205]
	v_pk_add_f32 v[14:15], v[178:179], v[14:15]
	v_pk_add_f32 v[64:65], v[180:181], v[64:65]
	v_pk_add_f32 v[14:15], v[182:183], v[14:15]
	v_pk_add_f32 v[64:65], v[184:185], v[64:65]
	v_pk_add_f32 v[14:15], v[186:187], v[14:15]
	v_pk_add_f32 v[64:65], v[200:201], v[64:65]
	v_cvt_pk_bf16_f32 v50, v66, v68
	v_pk_add_f32 v[14:15], v[14:15], v[64:65]
	v_cvt_pk_bf16_f32 v51, v67, v69
	v_cvt_pk_bf16_f32 v52, v78, v176
	v_cvt_pk_bf16_f32 v53, v79, v177
	v_cvt_pk_bf16_f32 v54, v178, v180
	v_cvt_pk_bf16_f32 v55, v179, v181
	v_cvt_pk_bf16_f32 v56, v70, v72
	v_cvt_pk_bf16_f32 v57, v71, v73
	v_cvt_pk_bf16_f32 v58, v74, v76
	v_cvt_pk_bf16_f32 v59, v75, v77
	v_cvt_pk_bf16_f32 v60, v182, v184
	v_cvt_pk_bf16_f32 v61, v183, v185
	v_cvt_pk_bf16_f32 v62, v186, v200
	v_cvt_pk_bf16_f32 v63, v187, v201
	v_add_f32_e32 v0, v14, v15
	s_setprio 1
	v_mfma_f32_32x32x16_bf16 v[16:31], v[136:139], v[48:51], v[16:31]
	v_add_f32_e32 v151, v151, v0
	v_mfma_f32_32x32x16_bf16 v[32:47], v[140:143], v[48:51], v[32:47]
	s_xor_b32 s11, s11, 1
	s_mul_i32 s12, s11, 0x3400
	v_mfma_f32_32x32x16_bf16 v[16:31], v[108:111], v[56:59], v[16:31]
	v_add_u32_e32 v241, s12, v217
	s_waitcnt vmcnt(4)
	ds_write_b128 v241, v[88:91]
	v_mfma_f32_32x32x16_bf16 v[32:47], v[132:135], v[56:59], v[32:47]
	v_add_u32_e32 v241, s12, v218
	s_waitcnt vmcnt(3)
	ds_write_b128 v241, v[84:87]
	v_mfma_f32_32x32x16_bf16 v[16:31], v[100:103], v[52:55], v[16:31]
	v_add_u32_e32 v241, s12, v219
	s_lshl_b32 s11, s11, 12
	s_waitcnt vmcnt(2)
	ds_write_b128 v241, v[10:13]
	s_sub_i32 s11, s12, s11
	v_mfma_f32_32x32x16_bf16 v[32:47], v[104:107], v[52:55], v[32:47]
	v_add_u32_e32 v241, s11, v220
	s_waitcnt vmcnt(1)
	ds_write_b128 v241, v[6:9] offset:26624
	s_add_i32 s9, s9, 64
	s_add_i32 s10, s10, 1
	v_mfma_f32_32x32x16_bf16 v[16:31], v[96:99], v[60:63], v[16:31]
	v_add_u32_e32 v241, s11, v221
	v_lshl_add_u64 v[162:163], v[162:163], 0, s[34:35]
	v_lshl_add_u64 v[164:165], v[164:165], 0, s[34:35]
	v_lshl_add_u64 v[166:167], v[166:167], 0, s[36:37]
	v_lshl_add_u64 v[168:169], v[168:169], 0, s[36:37]
	s_cmp_eq_u32 s2, s9
	v_lshl_add_u64 v[170:171], v[170:171], 0, s[36:37]
	s_waitcnt vmcnt(0)
	ds_write_b128 v241, v[2:5] offset:26624
	v_mfma_f32_32x32x16_bf16 v[32:47], v[92:95], v[60:63], v[32:47]
	s_setprio 0
	s_branch .Lmla_sync

; template <int DK, int MODE> ...
;     ...
;     if (more) swrite(cur ^ 1);
;     if (MODE == 2) { const int done = __all(R == 0.f); if (lane == 0) sFlag[cur * 4 + wave] = done; }
;     __syncthreads();
;     if (MODE == 2) { if (sFlag[cur * 4] & sFlag[cur * 4 + 1] & sFlag[cur * 4 + 2] & sFlag[cur * 4 + 3]) break; }
;   }
.Lmla_sync:
	s_waitcnt lgkmcnt(0)
	s_barrier
	s_cbranch_scc1 .LBB0_531

; __global__ void __launch_bounds__(256, 2) mega(Params p_unused) {
;   __shared__ __attribute__((aligned(16))) char smem[SMEM_BYTES];
	.amdhsa_kernel _Z4mega6Params
		.amdhsa_group_segment_fixed_size 74752
		.amdhsa_private_segment_fixed_size 0
		.amdhsa_kernarg_size 648
		.amdhsa_user_sgpr_count 2
		.amdhsa_user_sgpr_dispatch_ptr 0
		.amdhsa_user_sgpr_queue_ptr 0
		.amdhsa_user_sgpr_kernarg_segment_ptr 1
		.amdhsa_user_sgpr_dispatch_id 0
		.amdhsa_user_sgpr_kernarg_preload_length 0
		.amdhsa_user_sgpr_kernarg_preload_offset 0
		.amdhsa_user_sgpr_private_segment_size 0
		.amdhsa_uses_dynamic_stack 0
		.amdhsa_enable_private_segment 0
		.amdhsa_system_sgpr_workgroup_id_x 1
		.amdhsa_system_sgpr_workgroup_id_y 0
		.amdhsa_system_sgpr_workgroup_id_z 0
		.amdhsa_system_sgpr_workgroup_info 0
		.amdhsa_system_vgpr_workitem_id 2
		.amdhsa_next_free_vgpr 248
		.amdhsa_next_free_sgpr 102
		.amdhsa_accum_offset 248
		.amdhsa_reserve_vcc 1
		.amdhsa_float_round_mode_32 0
		.amdhsa_float_round_mode_16_64 0
		.amdhsa_float_denorm_mode_32 3
		.amdhsa_float_denorm_mode_16_64 3
		.amdhsa_dx10_clamp 1
		.amdhsa_ieee_mode 1
		.amdhsa_fp16_overflow 0
		.amdhsa_tg_split 0
		.amdhsa_exception_fp_ieee_invalid_op 0
		.amdhsa_exception_fp_denorm_src 0
		.amdhsa_exception_fp_ieee_div_zero 0
		.amdhsa_exception_fp_ieee_overflow 0
		.amdhsa_exception_fp_ieee_underflow 0
		.amdhsa_exception_fp_ieee_inexact 0
		.amdhsa_exception_int_div_zero 0
	.end_amdhsa_kernel

; __global__ void __launch_bounds__(256, 2) mega(Params p_unused) {
;   __shared__ __attribute__((aligned(16))) char smem[SMEM_BYTES];
amdhsa.kernels:
  - .agpr_count:     0
    .args:
      - .offset:         0
        .size:           392
        .value_kind:     by_value
      - .offset:         392
        .size:           4
        .value_kind:     hidden_block_count_x
      - .offset:         396
        .size:           4
        .value_kind:     hidden_block_count_y
      - .offset:         400
        .size:           4
        .value_kind:     hidden_block_count_z
      - .offset:         404
        .size:           2
        .value_kind:     hidden_group_size_x
      - .offset:         406
        .size:           2
        .value_kind:     hidden_group_size_y
      - .offset:         408
        .size:           2
        .value_kind:     hidden_group_size_z
      - .offset:         410
        .size:           2
        .value_kind:     hidden_remainder_x
      - .offset:         412
        .size:           2
        .value_kind:     hidden_remainder_y
      - .offset:         414
        .size:           2
        .value_kind:     hidden_remainder_z
      - .offset:         432
        .size:           8
        .value_kind:     hidden_global_offset_x
      - .offset:         440
        .size:           8
        .value_kind:     hidden_global_offset_y
      - .offset:         448
        .size:           8
        .value_kind:     hidden_global_offset_z
      - .offset:         456
        .size:           2
        .value_kind:     hidden_grid_dims
      - .offset:         480
        .size:           8
        .value_kind:     hidden_multigrid_sync_arg
    .group_segment_fixed_size: 74752
    .kernarg_segment_align: 8
    .kernarg_segment_size: 648
    .language:       OpenCL C
    .language_version:
      - 2
      - 0
    .max_flat_workgroup_size: 256
    .name:           _Z4mega6Params
    .private_segment_fixed_size: 0
    .sgpr_count:     108
    .sgpr_spill_count: 74
    .symbol:         _Z4mega6Params.kd
    .uniform_work_group_size: 1
    .uses_dynamic_stack: false
    .vgpr_count:     248
    .vgpr_spill_count: 0
    .wavefront_size: 64
